# speedup vs baseline: 1.0230x; 1.0130x over previous
.LBB0_408:
	ds_read_b128 v[70:73], v200 offset:50176
	ds_read_b128 v[66:69], v200 offset:58880
	ds_read_b128 v[178:181], v200 offset:50208
	ds_read_b128 v[212:215], v200 offset:58912
	ds_read_b128 v[242:245], v200 offset:50240
	ds_read_b128 v[246:249], v200 offset:58944
	v_exp_f32_e32 v166, v166
	v_exp_f32_e32 v175, v175
	v_exp_f32_e32 v167, v167
	v_exp_f32_e32 v176, v176
	s_waitcnt lgkmcnt(4)
	v_mfma_f32_32x32x16_bf16 v[82:97], v[70:73], v[142:145], 0
	v_exp_f32_e32 v168, v168
	v_exp_f32_e32 v177, v177
	v_exp_f32_e32 v169, v169
	v_exp_f32_e32 v174, v174
	v_mfma_f32_32x32x16_bf16 v[66:81], v[66:69], v[142:145], 0
	v_exp_f32_e32 v165, v165
	v_exp_f32_e32 v170, v170
	v_exp_f32_e32 v171, v171
	s_waitcnt lgkmcnt(2)
	v_mfma_f32_32x32x16_bf16 v[66:81], v[212:215], v[138:141], v[66:81]
	v_exp_f32_e32 v172, v172
	v_exp_f32_e32 v162, v162
	v_exp_f32_e32 v164, v164
	v_exp_f32_e32 v163, v163
	v_mfma_f32_32x32x16_bf16 v[82:97], v[178:181], v[138:141], v[82:97]
	ds_read_b128 v[178:181], v200 offset:50272
	ds_read_b128 v[212:215], v200 offset:58976
	v_exp_f32_e32 v173, v173
	v_exp_f32_e32 v0, v160
	v_exp_f32_e32 v160, v161
	s_waitcnt lgkmcnt(2)
	v_mfma_f32_32x32x16_bf16 v[66:81], v[246:249], v[134:137], v[66:81]
	v_add_f32_e32 v161, 0, v166
	v_add_f32_e32 v161, v175, v161
	v_add_f32_e32 v161, v167, v161
	v_add_f32_e32 v161, v176, v161
	v_mfma_f32_32x32x16_bf16 v[82:97], v[242:245], v[134:137], v[82:97]
	ds_read_b128 v[242:245], v200 offset:50304
	ds_read_b128 v[246:249], v200 offset:59008
	v_add_f32_e32 v161, v168, v161
	v_add_f32_e32 v161, v177, v161
	v_add_f32_e32 v161, v169, v161
	s_waitcnt lgkmcnt(2)
	v_mfma_f32_32x32x16_bf16 v[66:81], v[212:215], v[130:133], v[66:81]
	v_add_f32_e32 v161, v174, v161
	v_add_f32_e32 v161, v165, v161
	v_add_f32_e32 v161, v170, v161
	v_add_f32_e32 v161, v171, v161
	v_mfma_f32_32x32x16_bf16 v[82:97], v[178:181], v[130:133], v[82:97]
	ds_read_b128 v[178:181], v200 offset:50336
	ds_read_b128 v[212:215], v200 offset:59040
	v_add_f32_e32 v161, v172, v161
	v_add_f32_e32 v161, v162, v161
	v_add_f32_e32 v161, v164, v161
	v_exp_f32_e32 v158, v158
	s_waitcnt lgkmcnt(2)
	v_mfma_f32_32x32x16_bf16 v[66:81], v[246:249], v[126:129], v[66:81]
	v_add_f32_e32 v161, v163, v161
	v_exp_f32_e32 v159, v159
	v_add_f32_e32 v161, v173, v161
	v_mfma_f32_32x32x16_bf16 v[82:97], v[242:245], v[126:129], v[82:97]
	ds_read_b128 v[242:245], v200 offset:50368
	ds_read_b128 v[246:249], v200 offset:59072
	v_exp_f32_e32 v154, v154
	v_add_f32_e32 v161, v0, v161
	v_exp_f32_e32 v155, v155
	v_add_f32_e32 v161, v160, v161
	s_waitcnt lgkmcnt(2)
	v_mfma_f32_32x32x16_bf16 v[66:81], v[212:215], v[122:125], v[66:81]
	v_exp_f32_e32 v150, v150
	v_add_f32_e32 v161, v158, v161
	v_exp_f32_e32 v151, v151
	v_mfma_f32_32x32x16_bf16 v[82:97], v[178:181], v[122:125], v[82:97]
	ds_read_b128 v[178:181], v200 offset:50400
	ds_read_b128 v[212:215], v200 offset:59104
	v_add_f32_e32 v161, v159, v161
	v_exp_f32_e32 v146, v146
	v_add_f32_e32 v161, v154, v161
	v_exp_f32_e32 v147, v147
	s_waitcnt lgkmcnt(2)
	v_mfma_f32_32x32x16_bf16 v[66:81], v[246:249], v[118:121], v[66:81]
	v_add_f32_e32 v161, v155, v161
	v_exp_f32_e32 v156, v156
	v_add_f32_e32 v161, v150, v161
	v_mfma_f32_32x32x16_bf16 v[82:97], v[242:245], v[118:121], v[82:97]
	ds_read_b128 v[242:245], v205
	ds_read_b128 v[246:249], v205 offset:4608
	v_exp_f32_e32 v157, v157
	v_add_f32_e32 v161, v151, v161
	v_exp_f32_e32 v152, v152
	v_add_f32_e32 v161, v146, v161
	s_waitcnt lgkmcnt(2)
	v_mfma_f32_32x32x16_bf16 v[66:81], v[212:215], v[110:113], v[66:81]
	v_exp_f32_e32 v153, v153
	v_add_f32_e32 v161, v147, v161
	v_exp_f32_e32 v148, v148
	v_add_f32_e32 v161, v156, v161
	v_mfma_f32_32x32x16_bf16 v[82:97], v[178:181], v[110:113], v[82:97]
	ds_read_b128 v[178:181], v205 offset:32
	ds_read_b128 v[212:215], v205 offset:4640
	v_exp_f32_e32 v149, v149
	v_add_f32_e32 v161, v157, v161
	v_add_f32_e32 v161, v152, v161
	s_waitcnt lgkmcnt(2)
	v_mfma_f32_32x32x16_bf16 v[66:81], v[246:249], v[114:117], v[66:81]
	v_add_f32_e32 v161, v153, v161
	v_add_f32_e32 v161, v148, v161
	v_add_f32_e32 v211, v149, v161
	v_cvt_pk_bf16_f32 v166, v166, v175
	v_mfma_f32_32x32x16_bf16 v[82:97], v[242:245], v[114:117], v[82:97]
	ds_read_b128 v[242:245], v205 offset:64
	ds_read_b128 v[246:249], v205 offset:4672
	v_cvt_pk_bf16_f32 v167, v167, v176
	v_cvt_pk_bf16_f32 v168, v168, v177
	v_cvt_pk_bf16_f32 v169, v169, v174
	s_waitcnt lgkmcnt(2)
	v_mfma_f32_32x32x16_bf16 v[82:97], v[178:181], v[106:109], v[82:97]
	v_cvt_pk_bf16_f32 v170, v165, v170
	v_cvt_pk_bf16_f32 v171, v171, v172
	v_cvt_pk_bf16_f32 v172, v162, v164
	v_cvt_pk_bf16_f32 v173, v163, v173
	v_mfma_f32_32x32x16_bf16 v[66:81], v[212:215], v[106:109], v[66:81]
	ds_read_b128 v[178:181], v205 offset:96
	ds_read_b128 v[212:215], v205 offset:4704
	v_cvt_pk_bf16_f32 v174, v0, v160
	v_cvt_pk_bf16_f32 v175, v158, v159
	v_cvt_pk_bf16_f32 v176, v154, v155
	s_waitcnt lgkmcnt(2)
	v_mfma_f32_32x32x16_bf16 v[82:97], v[242:245], v[102:105], v[82:97]
	v_cvt_pk_bf16_f32 v177, v150, v151
	v_permlane32_swap_b32_e32 v166, v168
	v_permlane32_swap_b32_e32 v167, v169
	v_permlane32_swap_b32_e32 v170, v172
	v_mfma_f32_32x32x16_bf16 v[66:81], v[246:249], v[102:105], v[66:81]
	v_permlane32_swap_b32_e32 v171, v173
	v_permlane32_swap_b32_e32 v174, v176
	v_permlane32_swap_b32_e32 v175, v177
	s_waitcnt lgkmcnt(0)
	v_mfma_f32_32x32x16_bf16 v[82:97], v[178:181], v[98:101], v[82:97]
	v_cvt_pk_bf16_f32 v178, v146, v147
	v_cvt_pk_bf16_f32 v179, v156, v157
	v_cvt_pk_bf16_f32 v180, v152, v153
	v_cvt_pk_bf16_f32 v181, v148, v149
	s_nop 0
	v_permlane32_swap_b32_e32 v178, v180
	v_mfma_f32_32x32x16_bf16 v[66:81], v[212:215], v[98:101], v[66:81]
	v_mov_b32_e32 v212, v211
	s_nop 1
	v_permlane32_swap_b32_e32 v211, v212
	v_permlane32_swap_b32_e32 v179, v181
	ds_read_b64_tr_b16 v[214:215], v194 offset:0
	ds_read_b64_tr_b16 v[216:217], v194 offset:0x800
	ds_read_b64_tr_b16 v[218:219], v194 offset:0x1000
	ds_read_b64_tr_b16 v[220:221], v194 offset:0x1800
	ds_read_b64_tr_b16 v[222:223], v194 offset:0x2000
	ds_read_b64_tr_b16 v[224:225], v194 offset:0x2800
	ds_read_b64_tr_b16 v[226:227], v194 offset:0x3000
	ds_read_b64_tr_b16 v[228:229], v194 offset:0x3800
	s_add_u32 s74, s76, s96
	s_addc_u32 s75, s77, s97
	s_add_u32 s80, s88, s96
	s_addc_u32 s81, s89, s97
	s_add_u32 s8, s74, 0x1b988000
	s_addc_u32 s9, s75, 0
	s_add_u32 s10, s74, 0x1b98a000
	s_addc_u32 s11, s75, 0
	s_add_u32 s12, s80, 0x18884000
	s_addc_u32 s13, s81, 0
	s_add_u32 s14, s74, 0x1d988000
	s_addc_u32 s15, s75, 0
	s_add_u32 s16, s74, 0x1d98a000
	s_addc_u32 s17, s75, 0
	global_load_dwordx4 v[154:157], v201, s[8:9]
	global_load_dwordx4 v[158:161], v201, s[10:11]
	global_load_dwordx4 v[162:165], v199, s[12:13]
	global_load_dwordx4 v[146:149], v201, s[14:15]
	global_load_dwordx4 v[150:153], v201, s[16:17]
	s_sub_i32 s6, s70, 64
	s_cmp_le_i32 s6, s33
	s_cbranch_scc1 .LBB0_410
; __device__ __forceinline__ void mask_tile(f32x16& p0, f32x16& p1, int dq) {
;     const float NEG = -__builtin_inff();
; #pragma unroll
;     for (int r = 0; r < 16; ++r) { const int c = (r & 3) + 8 * (r >> 2);
;         if (dq - c < 0) p0[r] = NEG;
;         if (dq - c - 32 < 0) p1[r] = NEG; }
; }
; __device__ __forceinline__ void partialSM(f32x16& p0, f32x16& p1, float& m_reg, float& mn, float& alpha) {
;     float pmax = p0[0];
; #pragma unroll
;     for (int r = 1; r < 16; ++r) pmax = fmaxf(pmax, p0[r]);
; #pragma unroll
;     for (int r = 0; r < 16; ++r) pmax = fmaxf(pmax, p1[r]);
;     { auto rr = __builtin_amdgcn_permlane32_swap(__float_as_uint(pmax), __float_as_uint(pmax), false, false);
;       pmax = fmaxf(__uint_as_float(rr[0]), __uint_as_float(rr[1])); }
; template <int VB>
; __device__ __forceinline__ void pv_tile(f32x16* o, int vb0, bf16x8 pa0, bf16x8 pa1, bf16x8 pa2, bf16x8 pa3) {
;     ...
;     PV_D0(0); PV_D0(1); PV_D0(2); PV_D0(3);
	v_add_u32_e32 v0, 64, v209
	v_cmp_gt_i32_e64 s[64:65], 26, v0
	v_cmp_gt_i32_e64 s[66:67], 27, v0
	v_cmp_gt_i32_e64 s[62:63], 25, v0
	s_and_b64 s[64:65], s[66:67], s[64:65]
	v_cmp_gt_i32_e64 s[60:61], 24, v0
	s_and_b64 s[62:63], s[64:65], s[62:63]
	v_cmp_gt_i32_e64 s[58:59], 19, v0
	s_and_b64 s[60:61], s[62:63], s[60:61]
	v_cmp_gt_i32_e64 s[56:57], 18, v0
	s_and_b64 s[58:59], s[60:61], s[58:59]
	v_cmp_gt_i32_e64 s[54:55], 17, v0
	s_and_b64 s[56:57], s[58:59], s[56:57]
	v_cmp_gt_i32_e64 s[52:53], 16, v0
	s_and_b64 s[54:55], s[56:57], s[54:55]
	v_cmp_gt_i32_e64 s[50:51], 11, v0
	s_and_b64 s[52:53], s[54:55], s[52:53]
	v_cmp_gt_i32_e64 s[48:49], 10, v0
	s_and_b64 s[50:51], s[52:53], s[50:51]
	v_cmp_gt_i32_e64 s[46:47], 9, v0
	s_and_b64 s[48:49], s[50:51], s[48:49]
	v_cmp_gt_i32_e64 s[44:45], 8, v0
	s_and_b64 s[46:47], s[48:49], s[46:47]
	v_cmp_gt_i32_e64 s[42:43], 3, v0
	s_and_b64 s[44:45], s[46:47], s[44:45]
	v_cmp_gt_i32_e64 s[40:41], 2, v0
	s_and_b64 s[42:43], s[44:45], s[42:43]
	v_cmp_gt_i32_e64 s[38:39], 1, v0
	s_and_b64 s[40:41], s[42:43], s[40:41]
	v_cmp_gt_i32_e64 s[36:37], 0, v0
	s_and_b64 s[38:39], s[40:41], s[38:39]
	s_and_b64 s[36:37], s[38:39], s[36:37]
	v_cmp_gt_i32_e64 s[34:35], 58, v0
	v_cndmask_b32_e64 v82, v82, v186, s[36:37]
	v_cmp_gt_i32_e64 s[36:37], 59, v0
	v_cmp_gt_i32_e64 s[30:31], 57, v0
	s_and_b64 s[34:35], s[36:37], s[34:35]
	v_cmp_gt_i32_e64 s[28:29], 56, v0
	s_and_b64 s[30:31], s[34:35], s[30:31]
	v_cmp_gt_i32_e64 s[26:27], 51, v0
	s_and_b64 s[28:29], s[30:31], s[28:29]
	v_cmp_gt_i32_e64 s[24:25], 50, v0
	s_and_b64 s[26:27], s[28:29], s[26:27]
	v_cmp_gt_i32_e64 s[22:23], 49, v0
	s_and_b64 s[24:25], s[26:27], s[24:25]
	v_cmp_gt_i32_e64 s[20:21], 48, v0
	s_and_b64 s[22:23], s[24:25], s[22:23]
	v_cmp_gt_i32_e64 s[18:19], 43, v0
	s_and_b64 s[20:21], s[22:23], s[20:21]
	v_cmp_gt_i32_e64 s[16:17], 42, v0
	s_and_b64 s[18:19], s[20:21], s[18:19]
	v_cmp_gt_i32_e64 s[14:15], 41, v0
	s_and_b64 s[16:17], s[18:19], s[16:17]
	v_cmp_gt_i32_e64 s[12:13], 40, v0
	s_and_b64 s[14:15], s[16:17], s[14:15]
	v_cmp_gt_i32_e64 s[10:11], 35, v0
	s_and_b64 s[12:13], s[14:15], s[12:13]
	v_cmp_gt_i32_e64 s[8:9], 34, v0
	s_and_b64 s[10:11], s[12:13], s[10:11]
	v_cmp_gt_i32_e64 s[6:7], 33, v0
	s_and_b64 s[8:9], s[10:11], s[8:9]
	v_cmp_gt_i32_e32 vcc, 32, v0
	s_and_b64 s[6:7], s[8:9], s[6:7]
	s_and_b64 vcc, s[6:7], vcc
	v_cndmask_b32_e64 v97, v97, v186, s[66:67]
	v_cndmask_b32_e64 v96, v96, v186, s[64:65]
	v_cndmask_b32_e64 v95, v95, v186, s[62:63]
	v_cndmask_b32_e64 v94, v94, v186, s[60:61]
	v_cndmask_b32_e64 v93, v93, v186, s[58:59]
	v_cndmask_b32_e64 v92, v92, v186, s[56:57]
	v_cndmask_b32_e64 v91, v91, v186, s[54:55]
	v_cndmask_b32_e64 v90, v90, v186, s[52:53]
	v_cndmask_b32_e64 v89, v89, v186, s[50:51]
	v_cndmask_b32_e64 v88, v88, v186, s[48:49]
	v_cndmask_b32_e64 v87, v87, v186, s[46:47]
	v_cndmask_b32_e64 v86, v86, v186, s[44:45]
	v_cndmask_b32_e64 v85, v85, v186, s[42:43]
	v_cndmask_b32_e64 v84, v84, v186, s[40:41]
	v_cndmask_b32_e64 v83, v83, v186, s[38:39]
	v_cndmask_b32_e64 v81, v81, v186, s[36:37]
	v_cndmask_b32_e64 v80, v80, v186, s[34:35]
	v_cndmask_b32_e64 v79, v79, v186, s[30:31]
	v_cndmask_b32_e64 v78, v78, v186, s[28:29]
	v_cndmask_b32_e64 v77, v77, v186, s[26:27]
	v_cndmask_b32_e64 v76, v76, v186, s[24:25]
	v_cndmask_b32_e64 v75, v75, v186, s[22:23]
	v_cndmask_b32_e64 v74, v74, v186, s[20:21]
	v_cndmask_b32_e64 v73, v73, v186, s[18:19]
	v_cndmask_b32_e64 v72, v72, v186, s[16:17]
	v_cndmask_b32_e64 v71, v71, v186, s[14:15]
	v_cndmask_b32_e64 v70, v70, v186, s[12:13]
	v_cndmask_b32_e64 v69, v69, v186, s[10:11]
	v_cndmask_b32_e64 v68, v68, v186, s[8:9]
	v_cndmask_b32_e64 v67, v67, v186, s[6:7]
	v_cndmask_b32_e32 v66, v66, v186, vcc
.LBB0_410:
	s_nop 0
	s_waitcnt lgkmcnt(6)
	v_mfma_f32_32x32x16_bf16 v[50:65], v[166:169], v[214:217], v[50:65]
	ds_read_b64_tr_b16 v[214:215], v194 offset:0x200
	ds_read_b64_tr_b16 v[216:217], v194 offset:0xa00
	v_max_f32_e32 v0, v83, v83
	v_max_f32_e32 v190, v82, v82
	v_max_f32_e32 v0, v190, v0
	s_waitcnt lgkmcnt(6)
	v_mfma_f32_32x32x16_bf16 v[50:65], v[170:173], v[218:221], v[50:65]
	ds_read_b64_tr_b16 v[218:219], v194 offset:0x1200
	ds_read_b64_tr_b16 v[220:221], v194 offset:0x1a00
	v_max3_f32 v0, v0, v84, v85
	v_max3_f32 v0, v0, v86, v87
	s_waitcnt lgkmcnt(6)
	v_mfma_f32_32x32x16_bf16 v[50:65], v[174:177], v[222:225], v[50:65]
	ds_read_b64_tr_b16 v[222:223], v194 offset:0x2200
	ds_read_b64_tr_b16 v[224:225], v194 offset:0x2a00
	v_max3_f32 v0, v0, v88, v89
	v_max3_f32 v0, v0, v90, v91
	s_waitcnt lgkmcnt(6)
	v_mfma_f32_32x32x16_bf16 v[50:65], v[178:181], v[226:229], v[50:65]
	ds_read_b64_tr_b16 v[226:227], v194 offset:0x3200
	ds_read_b64_tr_b16 v[228:229], v194 offset:0x3a00
	v_max3_f32 v0, v0, v92, v93
	v_max3_f32 v0, v0, v94, v95
	v_max3_f32 v0, v0, v96, v97
	s_waitcnt lgkmcnt(6)
	v_mfma_f32_32x32x16_bf16 v[34:49], v[166:169], v[214:217], v[34:49]
	ds_read_b64_tr_b16 v[214:215], v194 offset:0x400
	ds_read_b64_tr_b16 v[216:217], v194 offset:0xc00
	v_max3_f32 v0, v0, v66, v67
	v_max3_f32 v0, v0, v68, v69
	s_waitcnt lgkmcnt(6)
	v_mfma_f32_32x32x16_bf16 v[34:49], v[170:173], v[218:221], v[34:49]
	ds_read_b64_tr_b16 v[218:219], v194 offset:0x1400
	ds_read_b64_tr_b16 v[220:221], v194 offset:0x1c00
	v_max3_f32 v0, v0, v70, v71
	v_max3_f32 v0, v0, v72, v73
	s_waitcnt lgkmcnt(6)
	v_mfma_f32_32x32x16_bf16 v[34:49], v[174:177], v[222:225], v[34:49]
	ds_read_b64_tr_b16 v[222:223], v194 offset:0x2400
	ds_read_b64_tr_b16 v[224:225], v194 offset:0x2c00
	v_max3_f32 v0, v0, v74, v75
	v_max3_f32 v0, v0, v76, v77
	v_max3_f32 v0, v0, v78, v79
	s_waitcnt lgkmcnt(6)
	v_mfma_f32_32x32x16_bf16 v[34:49], v[178:181], v[226:229], v[34:49]
	ds_read_b64_tr_b16 v[226:227], v194 offset:0x3400
	ds_read_b64_tr_b16 v[228:229], v194 offset:0x3c00
	v_max3_f32 v0, v0, v80, v81
	v_mov_b32_e32 v190, v0
	s_waitcnt lgkmcnt(6)
	v_mfma_f32_32x32x16_bf16 v[18:33], v[166:169], v[214:217], v[18:33]
	ds_read_b64_tr_b16 v[214:215], v194 offset:0x600
	ds_read_b64_tr_b16 v[216:217], v194 offset:0xe00
	s_nop 1
	v_permlane32_swap_b32_e32 v0, v190
	s_waitcnt lgkmcnt(6)
	v_mfma_f32_32x32x16_bf16 v[18:33], v[170:173], v[218:221], v[18:33]
	ds_read_b64_tr_b16 v[218:219], v194 offset:0x1600
	ds_read_b64_tr_b16 v[220:221], v194 offset:0x1e00
	v_max_f32_e32 v190, v190, v190
	v_max_f32_e32 v0, v0, v0
	v_max_f32_e32 v0, v0, v190
	s_waitcnt lgkmcnt(6)
	v_mfma_f32_32x32x16_bf16 v[18:33], v[174:177], v[222:225], v[18:33]
	ds_read_b64_tr_b16 v[222:223], v194 offset:0x2600
	ds_read_b64_tr_b16 v[224:225], v194 offset:0x2e00
	v_max_f32_e32 v191, v210, v210
	v_sub_f32_e32 v190, v0, v210
	s_waitcnt lgkmcnt(6)
	v_mfma_f32_32x32x16_bf16 v[18:33], v[178:181], v[226:229], v[18:33]
	ds_read_b64_tr_b16 v[226:227], v194 offset:0x3600
	ds_read_b64_tr_b16 v[228:229], v194 offset:0x3e00
	v_max_f32_e32 v0, v191, v0
	v_sub_f32_e32 v191, v210, v0
	s_waitcnt lgkmcnt(6)
	v_mfma_f32_32x32x16_bf16 v[2:17], v[166:169], v[214:217], v[2:17]
	s_waitcnt vmcnt(2)
	v_add_u32_e32 v192, 0x10800, v206
	ds_write_b128 v207, v[154:157] offset:32768
	ds_write_b128 v207, v[158:161] offset:41472
	ds_write_b128 v192, v[162:165]
	v_mul_f32_e32 v191, 0x3dd53b94, v191
	v_mul_f32_e32 v190, 0x3d93cd3a, v190
	v_exp_f32_e32 v191, v191
	s_waitcnt lgkmcnt(7)
	v_mfma_f32_32x32x16_bf16 v[2:17], v[170:173], v[218:221], v[2:17]
	s_mov_b32 s6, 0x41000000
	v_cmp_ge_f32_e32 vcc, s6, v190
	s_waitcnt lgkmcnt(5)
	v_mfma_f32_32x32x16_bf16 v[2:17], v[174:177], v[222:225], v[2:17]
	s_cmp_eq_u64 vcc, exec
	s_cselect_b64 s[6:7], -1, 0
	s_waitcnt lgkmcnt(3)
	v_mfma_f32_32x32x16_bf16 v[2:17], v[178:181], v[226:229], v[2:17]
	s_barrier
	s_waitcnt vmcnt(0)
	v_cndmask_b32_e64 v213, v191, 1.0, s[6:7]
	v_add_u32_e32 v214, 0, v206
	v_add_u32_e32 v166, 0x10800, v214
	v_cmp_gt_f32_e32 vcc, 1.0, v213
	s_waitcnt vmcnt(1)
	ds_write_b128 v202, v[146:149]
	s_waitcnt vmcnt(0)
	ds_write_b128 v203, v[150:153]
	s_cbranch_vccz .LBB0_414
	s_and_saveexec_b64 s[8:9], s[4:5]
	ds_write_b32 v195, v213 offset:128
	s_or_b64 exec, exec, s[8:9]
	s_waitcnt lgkmcnt(0)
	ds_read_b128 v[166:169], v198 offset:224
	ds_read_b128 v[170:173], v198 offset:192
	ds_read_b128 v[174:177], v198 offset:160
	ds_read_b128 v[178:181], v198 offset:128
	s_waitcnt lgkmcnt(3)
	v_pk_mul_f32 v[64:65], v[64:65], v[168:169]
	s_waitcnt lgkmcnt(2)
	v_pk_mul_f32 v[60:61], v[60:61], v[172:173]
	s_waitcnt lgkmcnt(1)
	v_pk_mul_f32 v[56:57], v[56:57], v[176:177]
	s_waitcnt lgkmcnt(0)
	v_pk_mul_f32 v[52:53], v[52:53], v[180:181]
	v_pk_mul_f32 v[62:63], v[62:63], v[166:167]
	v_pk_mul_f32 v[58:59], v[58:59], v[170:171]
	v_pk_mul_f32 v[54:55], v[54:55], v[174:175]
	v_pk_mul_f32 v[50:51], v[50:51], v[178:179]
	v_pk_mul_f32 v[48:49], v[48:49], v[168:169]
	v_pk_mul_f32 v[44:45], v[44:45], v[172:173]
	v_pk_mul_f32 v[40:41], v[40:41], v[176:177]
	v_pk_mul_f32 v[36:37], v[36:37], v[180:181]
	v_pk_mul_f32 v[46:47], v[46:47], v[166:167]
	v_pk_mul_f32 v[42:43], v[42:43], v[170:171]
	v_pk_mul_f32 v[38:39], v[38:39], v[174:175]
	v_pk_mul_f32 v[34:35], v[34:35], v[178:179]
	v_pk_mul_f32 v[32:33], v[32:33], v[168:169]
	v_pk_mul_f32 v[28:29], v[28:29], v[172:173]
	v_pk_mul_f32 v[24:25], v[24:25], v[176:177]
	v_pk_mul_f32 v[20:21], v[20:21], v[180:181]
	v_pk_mul_f32 v[30:31], v[30:31], v[166:167]
	v_pk_mul_f32 v[26:27], v[26:27], v[170:171]
	v_pk_mul_f32 v[22:23], v[22:23], v[174:175]
	v_pk_mul_f32 v[18:19], v[18:19], v[178:179]
	v_pk_mul_f32 v[16:17], v[16:17], v[168:169]
	v_pk_mul_f32 v[12:13], v[12:13], v[172:173]
	v_pk_mul_f32 v[8:9], v[8:9], v[176:177]
	v_pk_mul_f32 v[4:5], v[4:5], v[180:181]
	v_pk_mul_f32 v[14:15], v[14:15], v[166:167]
	v_pk_mul_f32 v[10:11], v[10:11], v[170:171]
	v_pk_mul_f32 v[6:7], v[6:7], v[174:175]
	v_pk_mul_f32 v[2:3], v[2:3], v[178:179]
.LBB0_414:
	v_cndmask_b32_e64 v210, v0, v210, s[6:7]
	v_mul_f32_e32 v181, 0xbdd53b94, v210
	v_fmamk_f32 v166, v82, 0x3dd53b94, v181
	v_fmamk_f32 v180, v83, 0x3dd53b94, v181
	v_fmamk_f32 v167, v84, 0x3dd53b94, v181
	v_fmamk_f32 v179, v85, 0x3dd53b94, v181
	v_fmamk_f32 v168, v86, 0x3dd53b94, v181
	v_fmamk_f32 v178, v87, 0x3dd53b94, v181
	v_fmamk_f32 v169, v88, 0x3dd53b94, v181
	v_fmamk_f32 v177, v89, 0x3dd53b94, v181
	v_fmamk_f32 v170, v90, 0x3dd53b94, v181
	v_fmamk_f32 v176, v91, 0x3dd53b94, v181
	v_fmamk_f32 v171, v92, 0x3dd53b94, v181
	v_fmamk_f32 v175, v93, 0x3dd53b94, v181
	v_fmamk_f32 v172, v94, 0x3dd53b94, v181
	v_fmamk_f32 v174, v95, 0x3dd53b94, v181
	v_fmamk_f32 v0, v96, 0x3dd53b94, v181
	v_fmamk_f32 v173, v97, 0x3dd53b94, v181
	v_fmamk_f32 v223, v66, 0x3dd53b94, v181
	v_fmamk_f32 v224, v67, 0x3dd53b94, v181
	v_fmamk_f32 v225, v68, 0x3dd53b94, v181
	v_fmamk_f32 v226, v69, 0x3dd53b94, v181
	v_fmamk_f32 v227, v70, 0x3dd53b94, v181
	v_fmamk_f32 v216, v71, 0x3dd53b94, v181
	v_fmamk_f32 v217, v72, 0x3dd53b94, v181
	v_fmamk_f32 v218, v73, 0x3dd53b94, v181
	v_fmamk_f32 v219, v74, 0x3dd53b94, v181
	v_fmamk_f32 v220, v75, 0x3dd53b94, v181
	v_fmamk_f32 v221, v76, 0x3dd53b94, v181
	v_fmamk_f32 v222, v77, 0x3dd53b94, v181
	v_fmamk_f32 v215, v78, 0x3dd53b94, v181
	v_fmamk_f32 v228, v79, 0x3dd53b94, v181
	v_fmamk_f32 v229, v80, 0x3dd53b94, v181
	v_fmac_f32_e32 v181, 0x3dd53b94, v81
	s_waitcnt lgkmcnt(0)
	s_barrier
; __device__ __forceinline__ void finishSM(f32x16& p0, f32x16& p1, float alpha, float& l_reg, bf16x8& pa0, bf16x8& pa1, bf16x8& pa2, bf16x8& pa3) {
; #pragma unroll
;     for (int r = 0; r < 16; ++r) p1[r] = __builtin_amdgcn_exp2f(p1[r]);
;     float ps = 0;
; #pragma unroll
;     for (int r = 0; r < 16; ++r) ps += p0[r];
; #pragma unroll
;     for (int r = 0; r < 16; ++r) ps += p1[r];
;     { auto rr = __builtin_amdgcn_permlane32_swap(__float_as_uint(ps), __float_as_uint(ps), false, false);
;       ps = __uint_as_float(rr[0]) + __uint_as_float(rr[1]); }
;     l_reg = l_reg * alpha + ps;
;     ...
;     PK4(p0, 0, pa0); PK4(p0, 8, pa1); PK4(p1, 0, pa2); PK4(p1, 8, pa3);
;     ...
; }
; template <int KB>
; __device__ __forceinline__ void qkt(f32x16& p0, f32x16& p1, const char* lds, int r32, int hi, const bf16x8* qr) {
;     p0 = f32x16{}; p1 = f32x16{};
;     const char* kb = lds + AO_K + KB * SHM_K + KSWZ(r32, hi * 16); const char* rb = lds + AO_R + KB * SHM_R + RSWZ(r32, hi * 16);
; #pragma unroll
;     for (int d0 = 0; d0 < 8; ++d0) { const char* a = kb + d0 * 32;
;         bf16x8 b0 = *reinterpret_cast<const bf16x8*>(a);
;         bf16x8 b1 = *reinterpret_cast<const bf16x8*>(a + 32 * KPITCH);
;         p0 = __builtin_amdgcn_mfma_f32_32x32x16_bf16(b0, qr[d0], p0, 0, 0, 0);
;         p1 = __builtin_amdgcn_mfma_f32_32x32x16_bf16(b1, qr[d0], p1, 0, 0, 0); }
; #pragma unroll
;     for (int d0 = 0; d0 < 4; ++d0) { const char* a = rb + d0 * 32;
;         bf16x8 b0 = *reinterpret_cast<const bf16x8*>(a);
;         bf16x8 b1 = *reinterpret_cast<const bf16x8*>(a + 32 * RPITCH);
;         p0 = __builtin_amdgcn_mfma_f32_32x32x16_bf16(b0, qr[8 + d0], p0, 0, 0, 0);
;         p1 = __builtin_amdgcn_mfma_f32_32x32x16_bf16(b1, qr[8 + d0], p1, 0, 0, 0); }
; }
	ds_read_b128 v[70:73], v200 offset:32768
	ds_read_b128 v[66:69], v200 offset:41472
	ds_read_b128 v[230:233], v200 offset:32800
	ds_read_b128 v[234:237], v200 offset:41504
	ds_read_b128 v[242:245], v200 offset:32832
	ds_read_b128 v[246:249], v200 offset:41536
	v_exp_f32_e32 v166, v166
	v_exp_f32_e32 v180, v180
	v_exp_f32_e32 v167, v167
	v_exp_f32_e32 v179, v179
	s_waitcnt lgkmcnt(4)
	v_mfma_f32_32x32x16_bf16 v[82:97], v[70:73], v[142:145], 0
	v_exp_f32_e32 v168, v168
	v_exp_f32_e32 v178, v178
	v_exp_f32_e32 v169, v169
	v_exp_f32_e32 v177, v177
	v_mfma_f32_32x32x16_bf16 v[66:81], v[66:69], v[142:145], 0
	v_exp_f32_e32 v170, v170
	v_exp_f32_e32 v176, v176
	v_exp_f32_e32 v171, v171
	v_exp_f32_e32 v175, v175
	s_waitcnt lgkmcnt(2)
	v_mfma_f32_32x32x16_bf16 v[66:81], v[234:237], v[138:141], v[66:81]
	v_exp_f32_e32 v172, v172
	v_exp_f32_e32 v174, v174
	v_exp_f32_e32 v173, v173
	v_exp_f32_e32 v0, v0
	v_mfma_f32_32x32x16_bf16 v[82:97], v[230:233], v[138:141], v[82:97]
	ds_read_b128 v[230:233], v200 offset:32864
	ds_read_b128 v[234:237], v200 offset:41568
	v_exp_f32_e32 v192, v225
	v_exp_f32_e32 v225, v215
	v_add_f32_e32 v215, 0, v166
	v_add_f32_e32 v215, v180, v215
	s_waitcnt lgkmcnt(2)
	v_mfma_f32_32x32x16_bf16 v[66:81], v[246:249], v[134:137], v[66:81]
	v_add_f32_e32 v215, v167, v215
	v_add_f32_e32 v215, v179, v215
	v_add_f32_e32 v215, v168, v215
	v_add_f32_e32 v215, v178, v215
	v_mfma_f32_32x32x16_bf16 v[82:97], v[242:245], v[134:137], v[82:97]
	ds_read_b128 v[242:245], v200 offset:32896
	ds_read_b128 v[246:249], v200 offset:41600
	v_add_f32_e32 v215, v169, v215
	v_add_f32_e32 v215, v177, v215
	v_add_f32_e32 v215, v170, v215
	v_add_f32_e32 v215, v176, v215
	s_waitcnt lgkmcnt(2)
	v_mfma_f32_32x32x16_bf16 v[66:81], v[234:237], v[130:133], v[66:81]
	v_add_f32_e32 v215, v171, v215
	v_add_f32_e32 v215, v175, v215
	v_exp_f32_e32 v190, v223
	v_add_f32_e32 v215, v172, v215
	v_mfma_f32_32x32x16_bf16 v[82:97], v[230:233], v[130:133], v[82:97]
	ds_read_b128 v[230:233], v200 offset:32928
	ds_read_b128 v[234:237], v200 offset:41632
	v_exp_f32_e32 v191, v224
	v_add_f32_e32 v215, v174, v215
	v_add_f32_e32 v215, v0, v215
	v_exp_f32_e32 v193, v226
	s_waitcnt lgkmcnt(2)
	v_mfma_f32_32x32x16_bf16 v[66:81], v[246:249], v[126:129], v[66:81]
	v_add_f32_e32 v215, v173, v215
	v_exp_f32_e32 v223, v227
	v_add_f32_e32 v215, v190, v215
	v_exp_f32_e32 v224, v216
	v_mfma_f32_32x32x16_bf16 v[82:97], v[242:245], v[126:129], v[82:97]
	ds_read_b128 v[242:245], v200 offset:32960
	ds_read_b128 v[246:249], v200 offset:41664
	v_add_f32_e32 v215, v191, v215
	v_exp_f32_e32 v217, v217
	v_add_f32_e32 v215, v192, v215
	v_exp_f32_e32 v218, v218
	s_waitcnt lgkmcnt(2)
	v_mfma_f32_32x32x16_bf16 v[66:81], v[234:237], v[122:125], v[66:81]
	v_add_f32_e32 v215, v193, v215
	v_exp_f32_e32 v219, v219
	v_add_f32_e32 v215, v223, v215
	v_mfma_f32_32x32x16_bf16 v[82:97], v[230:233], v[122:125], v[82:97]
	ds_read_b128 v[230:233], v200 offset:32992
	ds_read_b128 v[234:237], v200 offset:41696
	v_exp_f32_e32 v220, v220
	v_add_f32_e32 v215, v224, v215
	v_exp_f32_e32 v221, v221
	v_add_f32_e32 v215, v217, v215
	s_waitcnt lgkmcnt(2)
	v_mfma_f32_32x32x16_bf16 v[66:81], v[246:249], v[118:121], v[66:81]
	v_exp_f32_e32 v222, v222
	v_add_f32_e32 v215, v218, v215
	v_add_f32_e32 v215, v219, v215
	v_exp_f32_e32 v226, v228
	v_mfma_f32_32x32x16_bf16 v[82:97], v[242:245], v[118:121], v[82:97]
	ds_read_b128 v[242:245], v204
	ds_read_b128 v[246:249], v204 offset:4608
	v_add_f32_e32 v215, v220, v215
	v_exp_f32_e32 v227, v229
	v_add_f32_e32 v215, v221, v215
	v_exp_f32_e32 v181, v181
	s_waitcnt lgkmcnt(2)
	v_mfma_f32_32x32x16_bf16 v[66:81], v[234:237], v[110:113], v[66:81]
	v_add_f32_e32 v215, v222, v215
	v_add_f32_e32 v215, v225, v215
	v_add_f32_e32 v215, v226, v215
	v_add_f32_e32 v215, v227, v215
	v_mfma_f32_32x32x16_bf16 v[82:97], v[230:233], v[110:113], v[82:97]
	ds_read_b128 v[230:233], v204 offset:32
	ds_read_b128 v[234:237], v204 offset:4640
	v_add_f32_e32 v215, v181, v215
	v_mov_b32_e32 v216, v215
	v_cvt_pk_bf16_f32 v166, v166, v180
	v_cvt_pk_bf16_f32 v167, v167, v179
	s_waitcnt lgkmcnt(2)
	v_mfma_f32_32x32x16_bf16 v[66:81], v[246:249], v[114:117], v[66:81]
	v_cvt_pk_bf16_f32 v168, v168, v178
	v_cvt_pk_bf16_f32 v169, v169, v177
	v_cvt_pk_bf16_f32 v170, v170, v176
	v_cvt_pk_bf16_f32 v171, v171, v175
	v_mfma_f32_32x32x16_bf16 v[82:97], v[242:245], v[114:117], v[82:97]
	ds_read_b128 v[242:245], v204 offset:64
	ds_read_b128 v[246:249], v204 offset:4672
	v_cvt_pk_bf16_f32 v172, v172, v174
	v_cvt_pk_bf16_f32 v173, v0, v173
	v_cvt_pk_bf16_f32 v174, v190, v191
	v_cvt_pk_bf16_f32 v175, v192, v193
	s_waitcnt lgkmcnt(2)
	v_mfma_f32_32x32x16_bf16 v[82:97], v[230:233], v[106:109], v[82:97]
	v_cvt_pk_bf16_f32 v176, v223, v224
	v_cvt_pk_bf16_f32 v177, v217, v218
	v_cvt_pk_bf16_f32 v178, v219, v220
	v_cvt_pk_bf16_f32 v179, v221, v222
	v_mfma_f32_32x32x16_bf16 v[66:81], v[234:237], v[106:109], v[66:81]
	ds_read_b128 v[230:233], v204 offset:96
	ds_read_b128 v[234:237], v204 offset:4704
	v_cvt_pk_bf16_f32 v180, v225, v226
	v_cvt_pk_bf16_f32 v181, v227, v181
	v_permlane32_swap_b32_e32 v215, v216
	v_permlane32_swap_b32_e32 v166, v168
	s_waitcnt lgkmcnt(2)
	v_mfma_f32_32x32x16_bf16 v[82:97], v[242:245], v[102:105], v[82:97]
	v_permlane32_swap_b32_e32 v167, v169
	v_permlane32_swap_b32_e32 v170, v172
	v_permlane32_swap_b32_e32 v171, v173
	v_permlane32_swap_b32_e32 v174, v176
	v_mfma_f32_32x32x16_bf16 v[66:81], v[246:249], v[102:105], v[66:81]
	v_permlane32_swap_b32_e32 v175, v177
	v_permlane32_swap_b32_e32 v178, v180
	v_permlane32_swap_b32_e32 v179, v181
	s_waitcnt lgkmcnt(0)
	v_mfma_f32_32x32x16_bf16 v[82:97], v[230:233], v[98:101], v[82:97]
	v_mfma_f32_32x32x16_bf16 v[66:81], v[234:237], v[98:101], v[66:81]
	ds_read_b64_tr_b16 v[218:219], v194 offset:0x4000
	ds_read_b64_tr_b16 v[220:221], v194 offset:0x4800
	ds_read_b64_tr_b16 v[222:223], v194 offset:0x5000
	ds_read_b64_tr_b16 v[224:225], v194 offset:0x5800
	ds_read_b64_tr_b16 v[226:227], v194 offset:0x6000
	ds_read_b64_tr_b16 v[228:229], v194 offset:0x6800
	ds_read_b64_tr_b16 v[230:231], v194 offset:0x7000
	ds_read_b64_tr_b16 v[232:233], v194 offset:0x7800
	s_add_i32 s6, s82, 1
	s_cmp_lt_u32 s6, s83
	s_cselect_b64 s[90:91], -1, 0
	s_cmp_ge_u32 s6, s83
	s_cbranch_scc1 .LBB0_416
	s_add_u32 s8, s74, 0x1b98c000
	s_addc_u32 s9, s75, 0
	s_add_u32 s10, s74, 0x1b98e000
	s_addc_u32 s11, s75, 0
	s_add_u32 s12, s80, 0x18886000
	s_addc_u32 s13, s81, 0
	s_add_u32 s14, s74, 0x1d98c000
	s_addc_u32 s15, s75, 0
	s_add_u32 s16, s74, 0x1d98e000
	s_addc_u32 s17, s75, 0
	global_load_dwordx4 v[154:157], v201, s[8:9]
	global_load_dwordx4 v[158:161], v201, s[10:11]
	global_load_dwordx4 v[162:165], v199, s[12:13]
	global_load_dwordx4 v[146:149], v201, s[14:15]
	global_load_dwordx4 v[150:153], v201, s[16:17]

.LBB0_418:
	s_nop 0
	s_waitcnt lgkmcnt(6)
	v_mfma_f32_32x32x16_bf16 v[50:65], v[166:169], v[218:221], v[50:65]
	ds_read_b64_tr_b16 v[218:219], v194 offset:0x4200
	ds_read_b64_tr_b16 v[220:221], v194 offset:0x4a00
	v_max_f32_e32 v0, v83, v83
	v_max_f32_e32 v190, v82, v82
	s_waitcnt lgkmcnt(6)
	v_mfma_f32_32x32x16_bf16 v[50:65], v[170:173], v[222:225], v[50:65]
	ds_read_b64_tr_b16 v[222:223], v194 offset:0x5200
	ds_read_b64_tr_b16 v[224:225], v194 offset:0x5a00
	v_max_f32_e32 v0, v190, v0
	v_max3_f32 v0, v0, v84, v85
	s_waitcnt lgkmcnt(6)
	v_mfma_f32_32x32x16_bf16 v[50:65], v[174:177], v[226:229], v[50:65]
	ds_read_b64_tr_b16 v[226:227], v194 offset:0x6200
	ds_read_b64_tr_b16 v[228:229], v194 offset:0x6a00
	v_max3_f32 v0, v0, v86, v87
	v_max3_f32 v0, v0, v88, v89
	s_waitcnt lgkmcnt(6)
	v_mfma_f32_32x32x16_bf16 v[50:65], v[178:181], v[230:233], v[50:65]
	ds_read_b64_tr_b16 v[230:231], v194 offset:0x7200
	ds_read_b64_tr_b16 v[232:233], v194 offset:0x7a00
	v_max3_f32 v0, v0, v90, v91
	v_max3_f32 v0, v0, v92, v93
	s_waitcnt lgkmcnt(6)
	v_mfma_f32_32x32x16_bf16 v[34:49], v[166:169], v[218:221], v[34:49]
	ds_read_b64_tr_b16 v[218:219], v194 offset:0x4400
	ds_read_b64_tr_b16 v[220:221], v194 offset:0x4c00
	v_max3_f32 v0, v0, v94, v95
	v_max3_f32 v0, v0, v96, v97
	s_waitcnt lgkmcnt(6)
	v_mfma_f32_32x32x16_bf16 v[34:49], v[170:173], v[222:225], v[34:49]
	ds_read_b64_tr_b16 v[222:223], v194 offset:0x5400
	ds_read_b64_tr_b16 v[224:225], v194 offset:0x5c00
	v_max3_f32 v0, v0, v66, v67
	v_max3_f32 v0, v0, v68, v69
	s_waitcnt lgkmcnt(6)
	v_mfma_f32_32x32x16_bf16 v[34:49], v[174:177], v[226:229], v[34:49]
	ds_read_b64_tr_b16 v[226:227], v194 offset:0x6400
	ds_read_b64_tr_b16 v[228:229], v194 offset:0x6c00
	v_max3_f32 v0, v0, v70, v71
	v_max3_f32 v0, v0, v72, v73
	s_waitcnt lgkmcnt(6)
	v_mfma_f32_32x32x16_bf16 v[34:49], v[178:181], v[230:233], v[34:49]
	ds_read_b64_tr_b16 v[230:231], v194 offset:0x7400
	ds_read_b64_tr_b16 v[232:233], v194 offset:0x7c00
	v_max3_f32 v0, v0, v74, v75
	v_max3_f32 v0, v0, v76, v77
	s_waitcnt lgkmcnt(6)
	v_mfma_f32_32x32x16_bf16 v[18:33], v[166:169], v[218:221], v[18:33]
	ds_read_b64_tr_b16 v[218:219], v194 offset:0x4600
	ds_read_b64_tr_b16 v[220:221], v194 offset:0x4e00
	v_max3_f32 v0, v0, v78, v79
	v_max3_f32 v0, v0, v80, v81
	s_waitcnt lgkmcnt(6)
	v_mfma_f32_32x32x16_bf16 v[18:33], v[170:173], v[222:225], v[18:33]
	ds_read_b64_tr_b16 v[222:223], v194 offset:0x5600
	ds_read_b64_tr_b16 v[224:225], v194 offset:0x5e00
	v_mov_b32_e32 v190, v0
	s_nop 1
	s_waitcnt lgkmcnt(6)
	v_mfma_f32_32x32x16_bf16 v[18:33], v[174:177], v[226:229], v[18:33]
	ds_read_b64_tr_b16 v[226:227], v194 offset:0x6600
	ds_read_b64_tr_b16 v[228:229], v194 offset:0x6e00
	v_permlane32_swap_b32_e32 v0, v190
	v_max_f32_e32 v190, v190, v190
	s_waitcnt lgkmcnt(6)
	v_mfma_f32_32x32x16_bf16 v[18:33], v[178:181], v[230:233], v[18:33]
	ds_read_b64_tr_b16 v[230:231], v194 offset:0x7600
	ds_read_b64_tr_b16 v[232:233], v194 offset:0x7e00
	v_max_f32_e32 v0, v0, v0
	v_max_f32_e32 v0, v0, v190
	s_waitcnt lgkmcnt(6)
	v_mfma_f32_32x32x16_bf16 v[2:17], v[166:169], v[218:221], v[2:17]
	s_and_b64 vcc, exec, s[90:91]
	s_cbranch_vccnz .Lkw2_do
	s_waitcnt lgkmcnt(0)
	s_branch .Lkw2_done
.Lkw2_do:
	s_waitcnt vmcnt(2)
	v_add_u32_e32 v192, 0x12c00, v206
	ds_write_b128 v207, v[154:157] offset:50176
	ds_write_b128 v207, v[158:161] offset:58880
	ds_write_b128 v192, v[162:165]
.Lkw2_done:
	v_sub_f32_e32 v190, v0, v210
	v_mul_f32_e32 v190, 0x3d93cd3a, v190
	s_waitcnt lgkmcnt(7)
	v_mfma_f32_32x32x16_bf16 v[2:17], v[170:173], v[222:225], v[2:17]
	s_mov_b32 s6, 0x41000000
	v_cmp_ge_f32_e32 vcc, s6, v190
	s_waitcnt lgkmcnt(5)
	v_mfma_f32_32x32x16_bf16 v[2:17], v[174:177], v[226:229], v[2:17]
	s_cmp_eq_u64 vcc, exec
	s_cselect_b64 s[6:7], -1, 0
	s_waitcnt lgkmcnt(3)
	v_mfma_f32_32x32x16_bf16 v[2:17], v[178:181], v[230:233], v[2:17]
	s_andn2_b64 vcc, exec, s[90:91]
	s_barrier
	s_cbranch_vccnz .LBB0_420
	s_waitcnt vmcnt(0)
	s_waitcnt vmcnt(1)
	ds_write_b128 v202, v[146:149] offset:16384
	s_waitcnt vmcnt(0)
	ds_write_b128 v203, v[150:153] offset:16384
